# GU K-loops: the 4 B0-fragment LDS reads of phases 1 and 3 are issued in the MFMA shadow of the preceding phase (after its 16th MFMA); P1/P3 waits tightened to vmcnt(6) so the staged tile is retired on
# speedup vs baseline: 1.0107x; 1.0107x over previous
; #define LAS __attribute__((address_space(3)))
; #define PG8_STAGE(bufoff, gbase, voff) do { _Pragma("unroll") for (int _i = 0; _i < 2; ++_i) \
;         __builtin_amdgcn_global_load_lds((const unsigned*)((const char*)(gbase) + (voff)[_i]), (LAS unsigned*)(lds + (bufoff) + ldsw + _i * 8192), 16, 0, 0); } while (0)
; #define PG8_LDA(dst, b, h) do { _Pragma("unroll") for (int m = 0; m < 4; ++m) _Pragma("unroll") for (int k = 0; k < 2; ++k) dst[m][k] = *(const LAS bf16x8*)(lds + PG8_SA(b, h) + aoff + m * 2048 + k * 1024); } while (0)
; #define PG8_LDB(dst, b, h) do { _Pragma("unroll") for (int n = 0; n < 2; ++n) _Pragma("unroll") for (int k = 0; k < 2; ++k) dst[n][k] = *(const LAS bf16x8*)(lds + PG8_SB(b, h) + boff + n * 2048 + k * 1024); } while (0)
; #define PG8_WAIT_V(n) asm volatile("s_waitcnt vmcnt(" #n ")" ::: "memory")
; #define PG8_WAIT_L(n) asm volatile("s_waitcnt lgkmcnt(" #n ")" ::: "memory")
; template <class Epi>
; __device__ __forceinline__ void gemm_phase(LAS unsigned char* lds, const int tid, const Gemm g, const StaticOrder& S, const Epi& E) {
;     ...
;     for (;;) {
;         const bool has_next = S.next(ui + 1, nxt);
;         const char* nA = has_next ? (const char*)g.A + (size_t)nxt.pm * tstepA + (size_t)(nxt.pn >> g.a_grp_shift) * g.a_grp_bytes : cA;
;         const char* nB = has_next ? (const char*)g.Bt + (size_t)nxt.pn * tstepB : cB;
;         for (int t = 0; t < nt; t += 2) {
;             const bool last = (t == nt - 2);
;             const char* a1 = cA + (size_t)(t + 1) * kstep;
;             const char* a2 = last ? nA : cA + (size_t)(t + 2) * kstep; const char* b2 = last ? nB : cB + (size_t)(t + 2) * kstep;
;             const char* a3 = a2 + kstep; const char* b3 = b2 + kstep;
;             if constexpr (Epi::SS_LDS) { if (last) {
;                 const char* sp = (const char*)E.ss + (size_t)cur.pm * (256 * 64) + (size_t)tid * 16;
;                 __builtin_amdgcn_global_load_lds((const unsigned*)sp, (LAS unsigned*)(lds + RS_OFF + ldsw), 16, 0, 0);
;                 __builtin_amdgcn_global_load_lds((const unsigned*)(sp + 8192), (LAS unsigned*)(lds + RS_OFF + 8192 + ldsw), 16, 0, 0); } }
;     ...
;             PG8_LDB(B0, 0, 0); PG8_LDB(B1, 0, 1); PG8_SCHED; PG8_LDA(At, 0, 0); PG8_STAGE(PG8_SA(1, 1), a1 + hstepA, voffA);
;             PG8_WAIT_V(8); PG8_WAIT_L(0); PG8_BAR; PG8_MMA(0, 0, At, B0); PG8_MMA(0, 1, At, B1); PG8_BAR; PG8_SCHED;
.Lzskip_1:
	s_and_b64 s[30:31], s[4:5], exec
	s_cselect_b32 s17, s21, s29
	s_cselect_b32 s19, s20, s28
	s_cselect_b32 s55, s23, s27
	s_cselect_b32 s56, s22, s26
	s_ashr_i32 s25, s24, 31
	s_lshl_b64 s[30:31], s[24:25], 14
	s_add_u32 s25, s26, 0x100
	s_addc_u32 s57, s27, 0
	v_lshl_add_u64 v[146:147], v[136:137], 0, s[30:31]
	s_add_u32 s26, s28, 0x40080
	v_mov_b32_e32 v0, 0
	v_mov_b32_e32 v1, 0
	v_lshl_add_u64 v[148:149], v[146:147], 0, s[14:15]
	s_addc_u32 s27, s29, 0
	s_mov_b32 s58, 0
	v_pk_mov_b32 v[2:3], v[0:1], v[0:1]
	v_pk_mov_b32 v[4:5], v[0:1], v[0:1]
	v_pk_mov_b32 v[6:7], v[0:1], v[0:1]
	v_pk_mov_b32 v[8:9], v[0:1], v[0:1]
	v_pk_mov_b32 v[10:11], v[0:1], v[0:1]
	v_pk_mov_b32 v[12:13], v[0:1], v[0:1]
	v_pk_mov_b32 v[14:15], v[0:1], v[0:1]
	v_pk_mov_b32 v[16:17], v[0:1], v[0:1]
	v_pk_mov_b32 v[18:19], v[0:1], v[0:1]
	v_pk_mov_b32 v[20:21], v[0:1], v[0:1]
	v_pk_mov_b32 v[22:23], v[0:1], v[0:1]
	v_pk_mov_b32 v[24:25], v[0:1], v[0:1]
	v_pk_mov_b32 v[26:27], v[0:1], v[0:1]
	v_pk_mov_b32 v[28:29], v[0:1], v[0:1]
	v_pk_mov_b32 v[30:31], v[0:1], v[0:1]
	v_pk_mov_b32 v[32:33], v[0:1], v[0:1]
	v_pk_mov_b32 v[34:35], v[0:1], v[0:1]
	v_pk_mov_b32 v[36:37], v[0:1], v[0:1]
	v_pk_mov_b32 v[38:39], v[0:1], v[0:1]
	v_pk_mov_b32 v[40:41], v[0:1], v[0:1]
	v_pk_mov_b32 v[42:43], v[0:1], v[0:1]
	v_pk_mov_b32 v[44:45], v[0:1], v[0:1]
	v_pk_mov_b32 v[46:47], v[0:1], v[0:1]
	v_pk_mov_b32 v[48:49], v[0:1], v[0:1]
	v_pk_mov_b32 v[50:51], v[0:1], v[0:1]
	v_pk_mov_b32 v[52:53], v[0:1], v[0:1]
	v_pk_mov_b32 v[54:55], v[0:1], v[0:1]
	v_pk_mov_b32 v[56:57], v[0:1], v[0:1]
	v_pk_mov_b32 v[58:59], v[0:1], v[0:1]
	v_pk_mov_b32 v[60:61], v[0:1], v[0:1]
	v_pk_mov_b32 v[62:63], v[0:1], v[0:1]
	v_pk_mov_b32 v[64:65], v[0:1], v[0:1]
	v_pk_mov_b32 v[66:67], v[0:1], v[0:1]
	v_pk_mov_b32 v[68:69], v[0:1], v[0:1]
	v_pk_mov_b32 v[70:71], v[0:1], v[0:1]
	v_pk_mov_b32 v[72:73], v[0:1], v[0:1]
	v_pk_mov_b32 v[74:75], v[0:1], v[0:1]
	v_pk_mov_b32 v[76:77], v[0:1], v[0:1]
	v_pk_mov_b32 v[78:79], v[0:1], v[0:1]
	v_pk_mov_b32 v[80:81], v[0:1], v[0:1]
	v_pk_mov_b32 v[82:83], v[0:1], v[0:1]
	v_pk_mov_b32 v[84:85], v[0:1], v[0:1]
	v_pk_mov_b32 v[86:87], v[0:1], v[0:1]
	v_pk_mov_b32 v[88:89], v[0:1], v[0:1]
	v_pk_mov_b32 v[90:91], v[0:1], v[0:1]
	v_pk_mov_b32 v[92:93], v[0:1], v[0:1]
	v_pk_mov_b32 v[94:95], v[0:1], v[0:1]
	v_pk_mov_b32 v[96:97], v[0:1], v[0:1]
	v_pk_mov_b32 v[98:99], v[0:1], v[0:1]
	v_pk_mov_b32 v[100:101], v[0:1], v[0:1]
	v_pk_mov_b32 v[102:103], v[0:1], v[0:1]
	v_pk_mov_b32 v[104:105], v[0:1], v[0:1]
	v_pk_mov_b32 v[106:107], v[0:1], v[0:1]
	v_pk_mov_b32 v[108:109], v[0:1], v[0:1]
	v_pk_mov_b32 v[110:111], v[0:1], v[0:1]
	v_pk_mov_b32 v[112:113], v[0:1], v[0:1]
	v_pk_mov_b32 v[114:115], v[0:1], v[0:1]
	v_pk_mov_b32 v[116:117], v[0:1], v[0:1]
	v_pk_mov_b32 v[118:119], v[0:1], v[0:1]
	v_pk_mov_b32 v[120:121], v[0:1], v[0:1]
	v_pk_mov_b32 v[122:123], v[0:1], v[0:1]
	v_pk_mov_b32 v[124:125], v[0:1], v[0:1]
	v_pk_mov_b32 v[126:127], v[0:1], v[0:1]
	v_add_u32_e32 v168, s51, v151
	ds_read_b128 v[156:159], v168
	ds_read_b128 v[160:163], v168 offset:1024
	ds_read_b128 v[164:167], v168 offset:2048
	ds_read_b128 v[168:171], v168 offset:3072
	s_branch .LBB0_264
.LBB0_263:
	v_add_u32_e32 v184, s52, v151
	ds_read_b128 v[172:175], v184
	ds_read_b128 v[176:179], v184 offset:1024
	ds_read_b128 v[180:183], v184 offset:2048
	ds_read_b128 v[184:187], v184 offset:3072
	s_add_i32 s58, s58, 2
	s_add_u32 s30, s26, 0xfffc0080
	s_addc_u32 s31, s27, -1
	s_and_b64 s[28:29], s[28:29], exec
	s_cselect_b32 s31, s17, s31
	s_cselect_b32 s30, s19, s30
	s_cselect_b32 s29, s55, s57
	s_cselect_b32 s28, s56, s25
	v_lshl_add_u64 v[220:221], s[26:27], 0, v[140:141]
	s_add_i32 m0, s41, 0xc000
	ds_read_b128 v[188:191], v153
	ds_read_b128 v[192:195], v153 offset:1024
	ds_read_b128 v[196:199], v153 offset:2048
	ds_read_b128 v[200:203], v153 offset:3072
	ds_read_b128 v[204:207], v153 offset:4096
	ds_read_b128 v[208:211], v153 offset:5120
	ds_read_b128 v[212:215], v153 offset:6144
	ds_read_b128 v[216:219], v153 offset:7168
	global_load_lds_dwordx4 v[220:221], off
	v_lshl_add_u64 v[220:221], s[26:27], 0, v[138:139]
	s_add_i32 m0, s41, 0xe000
	s_nop 0
	global_load_lds_dwordx4 v[220:221], off
	s_waitcnt vmcnt(6)
	s_waitcnt lgkmcnt(0)
	s_barrier
	s_setprio 1
	v_mfma_f32_16x16x32_bf16 v[120:123], v[156:159], v[188:191], v[120:123]
	v_mfma_f32_16x16x32_bf16 v[116:119], v[164:167], v[188:191], v[116:119]
	v_mfma_f32_16x16x32_bf16 v[108:111], v[156:159], v[196:199], v[108:111]
	v_mfma_f32_16x16x32_bf16 v[100:103], v[164:167], v[196:199], v[100:103]
	v_mfma_f32_16x16x32_bf16 v[92:95], v[156:159], v[204:207], v[92:95]
	v_mfma_f32_16x16x32_bf16 v[84:87], v[164:167], v[204:207], v[84:87]
	v_mfma_f32_16x16x32_bf16 v[76:79], v[156:159], v[212:215], v[76:79]
	v_mfma_f32_16x16x32_bf16 v[68:71], v[164:167], v[212:215], v[68:71]
	v_mfma_f32_16x16x32_bf16 v[120:123], v[160:163], v[192:195], v[120:123]
	v_mfma_f32_16x16x32_bf16 v[116:119], v[168:171], v[192:195], v[116:119]
	v_mfma_f32_16x16x32_bf16 v[108:111], v[160:163], v[200:203], v[108:111]
	v_mfma_f32_16x16x32_bf16 v[100:103], v[168:171], v[200:203], v[100:103]
	v_mfma_f32_16x16x32_bf16 v[92:95], v[160:163], v[208:211], v[92:95]
	v_mfma_f32_16x16x32_bf16 v[84:87], v[168:171], v[208:211], v[84:87]
	v_mfma_f32_16x16x32_bf16 v[76:79], v[160:163], v[216:219], v[76:79]
	v_mfma_f32_16x16x32_bf16 v[68:71], v[168:171], v[216:219], v[68:71]
	v_mfma_f32_16x16x32_bf16 v[124:127], v[172:175], v[188:191], v[124:127]
	v_mfma_f32_16x16x32_bf16 v[112:115], v[180:183], v[188:191], v[112:115]
	v_mfma_f32_16x16x32_bf16 v[104:107], v[172:175], v[196:199], v[104:107]
	v_mfma_f32_16x16x32_bf16 v[96:99], v[180:183], v[196:199], v[96:99]
	v_mfma_f32_16x16x32_bf16 v[88:91], v[172:175], v[204:207], v[88:91]
	v_mfma_f32_16x16x32_bf16 v[80:83], v[180:183], v[204:207], v[80:83]
	v_mfma_f32_16x16x32_bf16 v[72:75], v[172:175], v[212:215], v[72:75]
	v_mfma_f32_16x16x32_bf16 v[64:67], v[180:183], v[212:215], v[64:67]
	v_mfma_f32_16x16x32_bf16 v[124:127], v[176:179], v[192:195], v[124:127]
	v_mfma_f32_16x16x32_bf16 v[112:115], v[184:187], v[192:195], v[112:115]
	v_mfma_f32_16x16x32_bf16 v[104:107], v[176:179], v[200:203], v[104:107]
	v_mfma_f32_16x16x32_bf16 v[96:99], v[184:187], v[200:203], v[96:99]
	v_mfma_f32_16x16x32_bf16 v[88:91], v[176:179], v[208:211], v[88:91]
	v_mfma_f32_16x16x32_bf16 v[80:83], v[184:187], v[208:211], v[80:83]
	v_mfma_f32_16x16x32_bf16 v[72:75], v[176:179], v[216:219], v[72:75]
	v_mfma_f32_16x16x32_bf16 v[64:67], v[184:187], v[216:219], v[64:67]
	s_setprio 0
	s_barrier
; #define PG8_STAGE(bufoff, gbase, voff) do { _Pragma("unroll") for (int _i = 0; _i < 2; ++_i) \
;         __builtin_amdgcn_global_load_lds((const unsigned*)((const char*)(gbase) + (voff)[_i]), (LAS unsigned*)(lds + (bufoff) + ldsw + _i * 8192), 16, 0, 0); } while (0)
; #define PG8_LDA(dst, b, h) do { _Pragma("unroll") for (int m = 0; m < 4; ++m) _Pragma("unroll") for (int k = 0; k < 2; ++k) dst[m][k] = *(const LAS bf16x8*)(lds + PG8_SA(b, h) + aoff + m * 2048 + k * 1024); } while (0)
; #define PG8_LDB(dst, b, h) do { _Pragma("unroll") for (int n = 0; n < 2; ++n) _Pragma("unroll") for (int k = 0; k < 2; ++k) dst[n][k] = *(const LAS bf16x8*)(lds + PG8_SB(b, h) + boff + n * 2048 + k * 1024); } while (0)
; #define PG8_MMA(ai, bj, At, Bt) do { __builtin_amdgcn_s_setprio(1); _Pragma("unroll") for (int m = 0; m < 4; ++m) _Pragma("unroll") for (int n = 0; n < 2; ++n) _Pragma("unroll") for (int k = 0; k < 2; ++k) \
;         acc[ai][bj][m][n] = __builtin_amdgcn_mfma_f32_16x16x32_bf16(Bt[n][k], At[m][k], acc[ai][bj][m][n], 0, 0, 0); __builtin_amdgcn_s_setprio(0); } while (0)
; #define PG8_WAIT_V(n) asm volatile("s_waitcnt vmcnt(" #n ")" ::: "memory")
; #define PG8_WAIT_L(n) asm volatile("s_waitcnt lgkmcnt(" #n ")" ::: "memory")
; #define PG8_BAR __builtin_amdgcn_s_barrier()
; #define PG8_SCHED __builtin_amdgcn_sched_barrier(0)
; template <class Epi>
; __device__ __forceinline__ void gemm_phase(LAS unsigned char* lds, const int tid, const Gemm g, const StaticOrder& S, const Epi& E) {
;     ...
;             PG8_LDA(At, 0, 1); PG8_STAGE(PG8_SB(0, 0), b2, voffB); PG8_STAGE(PG8_SB(0, 1), b2 + hstepB, voffB); PG8_STAGE(PG8_SA(0, 0), a2, voffA);
;             PG8_WAIT_V(8); PG8_WAIT_L(0); PG8_BAR; PG8_MMA(1, 0, At, B0); PG8_MMA(1, 1, At, B1); PG8_BAR; PG8_SCHED;
;             PG8_LDB(B0, 1, 0); PG8_LDB(B1, 1, 1); PG8_SCHED; PG8_LDA(At, 1, 0); PG8_STAGE(PG8_SA(0, 1), a2 + hstepA, voffA);
;             PG8_WAIT_V(8); PG8_WAIT_L(0); PG8_BAR; PG8_MMA(0, 0, At, B0); PG8_MMA(0, 1, At, B1); PG8_BAR; PG8_SCHED;
	s_add_i32 s59, s51, s38
	v_lshl_add_u64 v[220:221], s[28:29], 0, v[132:133]
	s_mov_b32 m0, s59
	ds_read_b128 v[188:191], v153 offset:16384
	ds_read_b128 v[192:195], v153 offset:17408
	ds_read_b128 v[196:199], v153 offset:18432
	ds_read_b128 v[200:203], v153 offset:19456
	ds_read_b128 v[204:207], v153 offset:20480
	ds_read_b128 v[208:211], v153 offset:21504
	ds_read_b128 v[212:215], v153 offset:22528
	ds_read_b128 v[216:219], v153 offset:23552
	global_load_lds_dwordx4 v[220:221], off
	s_add_i32 m0, s59, 0x2000
	s_add_u32 s60, s28, 0x40000
	v_lshl_add_u64 v[222:223], s[28:29], 0, v[128:129]
	s_addc_u32 s61, s29, 0
	s_add_i32 s59, s52, s38
	global_load_lds_dwordx4 v[222:223], off
	v_lshl_add_u64 v[224:225], s[60:61], 0, v[132:133]
	s_mov_b32 m0, s59
	v_lshl_add_u64 v[226:227], s[30:31], 0, v[130:131]
	global_load_lds_dwordx4 v[224:225], off
	v_lshl_add_u64 v[224:225], s[60:61], 0, v[128:129]
	s_add_i32 m0, s59, 0x2000
	s_nop 0
	global_load_lds_dwordx4 v[224:225], off
	v_lshl_add_u64 v[224:225], s[30:31], 0, v[134:135]
	s_mov_b32 m0, s41
	s_nop 0
	global_load_lds_dwordx4 v[224:225], off
	s_mov_b32 m0, s42
	s_nop 0
	global_load_lds_dwordx4 v[226:227], off
	s_waitcnt vmcnt(8)
	s_waitcnt lgkmcnt(0)
	s_barrier
	s_setprio 1
	v_mfma_f32_16x16x32_bf16 v[60:63], v[156:159], v[188:191], v[60:63]
	v_mfma_f32_16x16x32_bf16 v[52:55], v[164:167], v[188:191], v[52:55]
	v_mfma_f32_16x16x32_bf16 v[44:47], v[156:159], v[196:199], v[44:47]
	v_mfma_f32_16x16x32_bf16 v[36:39], v[164:167], v[196:199], v[36:39]
	v_mfma_f32_16x16x32_bf16 v[28:31], v[156:159], v[204:207], v[28:31]
	v_mfma_f32_16x16x32_bf16 v[20:23], v[164:167], v[204:207], v[20:23]
	v_mfma_f32_16x16x32_bf16 v[12:15], v[156:159], v[212:215], v[12:15]
	v_mfma_f32_16x16x32_bf16 v[4:7], v[164:167], v[212:215], v[4:7]
	v_mfma_f32_16x16x32_bf16 v[60:63], v[160:163], v[192:195], v[60:63]
	v_mfma_f32_16x16x32_bf16 v[52:55], v[168:171], v[192:195], v[52:55]
	v_mfma_f32_16x16x32_bf16 v[44:47], v[160:163], v[200:203], v[44:47]
	v_mfma_f32_16x16x32_bf16 v[36:39], v[168:171], v[200:203], v[36:39]
	v_mfma_f32_16x16x32_bf16 v[28:31], v[160:163], v[208:211], v[28:31]
	v_mfma_f32_16x16x32_bf16 v[20:23], v[168:171], v[208:211], v[20:23]
	v_mfma_f32_16x16x32_bf16 v[12:15], v[160:163], v[216:219], v[12:15]
	v_mfma_f32_16x16x32_bf16 v[4:7], v[168:171], v[216:219], v[4:7]
	v_mfma_f32_16x16x32_bf16 v[56:59], v[172:175], v[188:191], v[56:59]
	v_add_u32_e32 v168, 0x18000, v151
	v_mfma_f32_16x16x32_bf16 v[48:51], v[180:183], v[188:191], v[48:51]
	v_mfma_f32_16x16x32_bf16 v[40:43], v[172:175], v[196:199], v[40:43]
	ds_read_b128 v[156:159], v168
	v_mfma_f32_16x16x32_bf16 v[32:35], v[180:183], v[196:199], v[32:35]
	v_mfma_f32_16x16x32_bf16 v[24:27], v[172:175], v[204:207], v[24:27]
	v_mfma_f32_16x16x32_bf16 v[16:19], v[180:183], v[204:207], v[16:19]
	ds_read_b128 v[160:163], v168 offset:1024
	v_mfma_f32_16x16x32_bf16 v[8:11], v[172:175], v[212:215], v[8:11]
	v_mfma_f32_16x16x32_bf16 v[0:3], v[180:183], v[212:215], v[0:3]
	v_mfma_f32_16x16x32_bf16 v[56:59], v[176:179], v[192:195], v[56:59]
	ds_read_b128 v[164:167], v168 offset:2048
	v_mfma_f32_16x16x32_bf16 v[48:51], v[184:187], v[192:195], v[48:51]
	v_mfma_f32_16x16x32_bf16 v[40:43], v[176:179], v[200:203], v[40:43]
	v_mfma_f32_16x16x32_bf16 v[32:35], v[184:187], v[200:203], v[32:35]
	ds_read_b128 v[168:171], v168 offset:3072
	v_mfma_f32_16x16x32_bf16 v[24:27], v[176:179], v[208:211], v[24:27]
	v_mfma_f32_16x16x32_bf16 v[16:19], v[184:187], v[208:211], v[16:19]
	v_mfma_f32_16x16x32_bf16 v[8:11], v[176:179], v[216:219], v[8:11]
	v_mfma_f32_16x16x32_bf16 v[0:3], v[184:187], v[216:219], v[0:3]
	s_setprio 0
	s_barrier
	s_add_i32 s59, 0, 0x18000
	s_add_i32 s60, 0, 0x1c000
	v_add_u32_e32 v184, s60, v151
	ds_read_b128 v[172:175], v184
	ds_read_b128 v[176:179], v184 offset:1024
	ds_read_b128 v[180:183], v184 offset:2048
	ds_read_b128 v[184:187], v184 offset:3072
	s_add_u32 s30, s30, 0x40000
	s_addc_u32 s31, s31, 0
	s_mov_b32 m0, s43
	v_lshl_add_u64 v[228:229], s[30:31], 0, v[134:135]
	ds_read_b128 v[188:191], v153 offset:32768
	ds_read_b128 v[192:195], v153 offset:33792
	ds_read_b128 v[196:199], v153 offset:34816
	ds_read_b128 v[200:203], v153 offset:35840
	ds_read_b128 v[204:207], v153 offset:36864
	ds_read_b128 v[208:211], v153 offset:37888
	ds_read_b128 v[212:215], v153 offset:38912
	ds_read_b128 v[216:219], v153 offset:39936
	global_load_lds_dwordx4 v[228:229], off
	v_lshl_add_u64 v[228:229], s[30:31], 0, v[130:131]
	s_mov_b32 m0, s44
	s_nop 0
	global_load_lds_dwordx4 v[228:229], off
	s_waitcnt vmcnt(6)
	s_waitcnt lgkmcnt(0)
	s_barrier
; #define PG8_STAGE(bufoff, gbase, voff) do { _Pragma("unroll") for (int _i = 0; _i < 2; ++_i) \
;         __builtin_amdgcn_global_load_lds((const unsigned*)((const char*)(gbase) + (voff)[_i]), (LAS unsigned*)(lds + (bufoff) + ldsw + _i * 8192), 16, 0, 0); } while (0)
; #define PG8_LDA(dst, b, h) do { _Pragma("unroll") for (int m = 0; m < 4; ++m) _Pragma("unroll") for (int k = 0; k < 2; ++k) dst[m][k] = *(const LAS bf16x8*)(lds + PG8_SA(b, h) + aoff + m * 2048 + k * 1024); } while (0)
; #define PG8_MMA(ai, bj, At, Bt) do { __builtin_amdgcn_s_setprio(1); _Pragma("unroll") for (int m = 0; m < 4; ++m) _Pragma("unroll") for (int n = 0; n < 2; ++n) _Pragma("unroll") for (int k = 0; k < 2; ++k) \
;         acc[ai][bj][m][n] = __builtin_amdgcn_mfma_f32_16x16x32_bf16(Bt[n][k], At[m][k], acc[ai][bj][m][n], 0, 0, 0); __builtin_amdgcn_s_setprio(0); } while (0)
; #define PG8_WAIT_V(n) asm volatile("s_waitcnt vmcnt(" #n ")" ::: "memory")
; #define PG8_WAIT_L(n) asm volatile("s_waitcnt lgkmcnt(" #n ")" ::: "memory")
; #define PG8_BAR __builtin_amdgcn_s_barrier()
; #define PG8_SCHED __builtin_amdgcn_sched_barrier(0)
; template <class Epi>
; __device__ __forceinline__ void gemm_phase(LAS unsigned char* lds, const int tid, const Gemm g, const StaticOrder& S, const Epi& E) {
;     ...
;             PG8_WAIT_V(8); PG8_WAIT_L(0); PG8_BAR; PG8_MMA(0, 0, At, B0); PG8_MMA(0, 1, At, B1); PG8_BAR; PG8_SCHED;
;             PG8_LDA(At, 1, 1); PG8_STAGE(PG8_SB(1, 0), b3, voffB); PG8_STAGE(PG8_SB(1, 1), b3 + hstepB, voffB); PG8_STAGE(PG8_SA(1, 0), a3, voffA);
;             PG8_WAIT_V(8); PG8_WAIT_L(0); PG8_BAR; PG8_MMA(1, 0, At, B0); PG8_MMA(1, 1, At, B1); PG8_BAR; PG8_SCHED;
	s_setprio 1
	v_mfma_f32_16x16x32_bf16 v[120:123], v[156:159], v[188:191], v[120:123]
	v_mfma_f32_16x16x32_bf16 v[116:119], v[164:167], v[188:191], v[116:119]
	v_mfma_f32_16x16x32_bf16 v[108:111], v[156:159], v[196:199], v[108:111]
	v_mfma_f32_16x16x32_bf16 v[100:103], v[164:167], v[196:199], v[100:103]
	v_mfma_f32_16x16x32_bf16 v[92:95], v[156:159], v[204:207], v[92:95]
	v_mfma_f32_16x16x32_bf16 v[84:87], v[164:167], v[204:207], v[84:87]
	v_mfma_f32_16x16x32_bf16 v[76:79], v[156:159], v[212:215], v[76:79]
	v_mfma_f32_16x16x32_bf16 v[68:71], v[164:167], v[212:215], v[68:71]
	v_mfma_f32_16x16x32_bf16 v[120:123], v[160:163], v[192:195], v[120:123]
	v_mfma_f32_16x16x32_bf16 v[116:119], v[168:171], v[192:195], v[116:119]
	v_mfma_f32_16x16x32_bf16 v[108:111], v[160:163], v[200:203], v[108:111]
	v_mfma_f32_16x16x32_bf16 v[100:103], v[168:171], v[200:203], v[100:103]
	v_mfma_f32_16x16x32_bf16 v[92:95], v[160:163], v[208:211], v[92:95]
	v_mfma_f32_16x16x32_bf16 v[84:87], v[168:171], v[208:211], v[84:87]
	v_mfma_f32_16x16x32_bf16 v[76:79], v[160:163], v[216:219], v[76:79]
	v_mfma_f32_16x16x32_bf16 v[68:71], v[168:171], v[216:219], v[68:71]
	v_mfma_f32_16x16x32_bf16 v[124:127], v[172:175], v[188:191], v[124:127]
	v_mfma_f32_16x16x32_bf16 v[112:115], v[180:183], v[188:191], v[112:115]
	v_mfma_f32_16x16x32_bf16 v[104:107], v[172:175], v[196:199], v[104:107]
	v_mfma_f32_16x16x32_bf16 v[96:99], v[180:183], v[196:199], v[96:99]
	v_mfma_f32_16x16x32_bf16 v[88:91], v[172:175], v[204:207], v[88:91]
	v_mfma_f32_16x16x32_bf16 v[80:83], v[180:183], v[204:207], v[80:83]
	v_mfma_f32_16x16x32_bf16 v[72:75], v[172:175], v[212:215], v[72:75]
	v_mfma_f32_16x16x32_bf16 v[64:67], v[180:183], v[212:215], v[64:67]
	v_mfma_f32_16x16x32_bf16 v[124:127], v[176:179], v[192:195], v[124:127]
	v_mfma_f32_16x16x32_bf16 v[112:115], v[184:187], v[192:195], v[112:115]
	v_mfma_f32_16x16x32_bf16 v[104:107], v[176:179], v[200:203], v[104:107]
	v_mfma_f32_16x16x32_bf16 v[96:99], v[184:187], v[200:203], v[96:99]
	v_mfma_f32_16x16x32_bf16 v[88:91], v[176:179], v[208:211], v[88:91]
	v_mfma_f32_16x16x32_bf16 v[80:83], v[184:187], v[208:211], v[80:83]
	v_mfma_f32_16x16x32_bf16 v[72:75], v[176:179], v[216:219], v[72:75]
	v_mfma_f32_16x16x32_bf16 v[64:67], v[184:187], v[216:219], v[64:67]
	s_setprio 0
	s_barrier
	s_add_i32 s30, s59, s38
	v_lshl_add_u64 v[220:221], v[220:221], 0, s[12:13]
	s_mov_b32 m0, s30
	ds_read_b128 v[188:191], v153 offset:49152
	ds_read_b128 v[192:195], v153 offset:50176
	ds_read_b128 v[196:199], v153 offset:51200
	ds_read_b128 v[200:203], v153 offset:52224
	ds_read_b128 v[204:207], v153 offset:53248
	ds_read_b128 v[208:211], v153 offset:54272
	ds_read_b128 v[212:215], v153 offset:55296
	ds_read_b128 v[216:219], v153 offset:56320
	global_load_lds_dwordx4 v[220:221], off
	s_add_i32 m0, s30, 0x2000
	s_add_u32 s28, s28, 0x40080
	v_lshl_add_u64 v[220:221], v[222:223], 0, s[12:13]
	s_addc_u32 s29, s29, 0
	s_add_i32 s30, s60, s38
	global_load_lds_dwordx4 v[220:221], off
	v_lshl_add_u64 v[220:221], s[28:29], 0, v[132:133]
	s_mov_b32 m0, s30
	s_nop 0
	global_load_lds_dwordx4 v[220:221], off
	v_lshl_add_u64 v[220:221], s[28:29], 0, v[128:129]
	s_add_i32 m0, s30, 0x2000
	s_nop 0
	global_load_lds_dwordx4 v[220:221], off
	v_lshl_add_u64 v[220:221], v[224:225], 0, s[12:13]
	s_mov_b32 m0, s47
	s_nop 0
	global_load_lds_dwordx4 v[220:221], off
	v_lshl_add_u64 v[220:221], v[226:227], 0, s[12:13]
	s_mov_b32 m0, s48
	s_nop 0
	global_load_lds_dwordx4 v[220:221], off
	s_add_u32 s25, s25, 0x100
	s_addc_u32 s57, s57, 0
	s_add_u32 s26, s26, 0x100
	s_addc_u32 s27, s27, 0
	s_cmp_eq_u32 s49, s58
	s_cselect_b64 s[28:29], -1, 0
	s_waitcnt vmcnt(8)
	s_waitcnt lgkmcnt(0)
	s_barrier
	s_setprio 1
	v_mfma_f32_16x16x32_bf16 v[60:63], v[156:159], v[188:191], v[60:63]
	v_mfma_f32_16x16x32_bf16 v[52:55], v[164:167], v[188:191], v[52:55]
	v_mfma_f32_16x16x32_bf16 v[44:47], v[156:159], v[196:199], v[44:47]
	v_mfma_f32_16x16x32_bf16 v[36:39], v[164:167], v[196:199], v[36:39]
	v_mfma_f32_16x16x32_bf16 v[28:31], v[156:159], v[204:207], v[28:31]
	v_mfma_f32_16x16x32_bf16 v[20:23], v[164:167], v[204:207], v[20:23]
	v_mfma_f32_16x16x32_bf16 v[12:15], v[156:159], v[212:215], v[12:15]
	v_mfma_f32_16x16x32_bf16 v[4:7], v[164:167], v[212:215], v[4:7]
	v_mfma_f32_16x16x32_bf16 v[60:63], v[160:163], v[192:195], v[60:63]
	v_mfma_f32_16x16x32_bf16 v[52:55], v[168:171], v[192:195], v[52:55]
	v_mfma_f32_16x16x32_bf16 v[44:47], v[160:163], v[200:203], v[44:47]
	v_mfma_f32_16x16x32_bf16 v[36:39], v[168:171], v[200:203], v[36:39]
	v_mfma_f32_16x16x32_bf16 v[28:31], v[160:163], v[208:211], v[28:31]
	v_mfma_f32_16x16x32_bf16 v[20:23], v[168:171], v[208:211], v[20:23]
	v_mfma_f32_16x16x32_bf16 v[12:15], v[160:163], v[216:219], v[12:15]
	v_mfma_f32_16x16x32_bf16 v[4:7], v[168:171], v[216:219], v[4:7]
	v_mfma_f32_16x16x32_bf16 v[56:59], v[172:175], v[188:191], v[56:59]
	v_add_u32_e32 v168, s51, v151
	v_mfma_f32_16x16x32_bf16 v[48:51], v[180:183], v[188:191], v[48:51]
	v_mfma_f32_16x16x32_bf16 v[40:43], v[172:175], v[196:199], v[40:43]
	ds_read_b128 v[156:159], v168
	v_mfma_f32_16x16x32_bf16 v[32:35], v[180:183], v[196:199], v[32:35]
	v_mfma_f32_16x16x32_bf16 v[24:27], v[172:175], v[204:207], v[24:27]
	v_mfma_f32_16x16x32_bf16 v[16:19], v[180:183], v[204:207], v[16:19]
	ds_read_b128 v[160:163], v168 offset:1024
	v_mfma_f32_16x16x32_bf16 v[8:11], v[172:175], v[212:215], v[8:11]
	v_mfma_f32_16x16x32_bf16 v[0:3], v[180:183], v[212:215], v[0:3]
	v_mfma_f32_16x16x32_bf16 v[56:59], v[176:179], v[192:195], v[56:59]
	ds_read_b128 v[164:167], v168 offset:2048
	v_mfma_f32_16x16x32_bf16 v[48:51], v[184:187], v[192:195], v[48:51]
	v_mfma_f32_16x16x32_bf16 v[40:43], v[176:179], v[200:203], v[40:43]
	v_mfma_f32_16x16x32_bf16 v[32:35], v[184:187], v[200:203], v[32:35]
	ds_read_b128 v[168:171], v168 offset:3072
	v_mfma_f32_16x16x32_bf16 v[24:27], v[176:179], v[208:211], v[24:27]
	v_mfma_f32_16x16x32_bf16 v[16:19], v[184:187], v[208:211], v[16:19]
	v_mfma_f32_16x16x32_bf16 v[8:11], v[176:179], v[216:219], v[8:11]
	v_mfma_f32_16x16x32_bf16 v[0:3], v[184:187], v[216:219], v[0:3]
	s_setprio 0
	s_barrier
	s_cmp_ge_i32 s58, s46
	s_cbranch_scc1 .LBB0_266
	s_cmp_lg_u32 s49, s58
	s_cbranch_scc1 .LBB0_263
	s_branch .Lrs_1
